# SB tile loop without the s_setprio raise/lower around its MFMA clusters (wave priority left at default)
# speedup vs baseline: 1.0074x; 1.0014x over previous
; DI float half_other(float x, int hh) { float a, b; half_swap(x, a, b); return hh ? a : b; }
; DI int crow(int reg, int hh) { return (reg & 3) + 8 * (reg >> 2) + 4 * hh; }
; DI float ex2(float x) { return __builtin_amdgcn_exp2f(x); }
; DI void sb_item(const bf16_t* __restrict__ P, const bf16_t* __restrict__ VT, bf16_t* __restrict__ Y, int item, char* lds) {
;     ...
;   auto do_tile = [&](int kb, const bf16_t* kcur) {
;     const bool active = (kb * 64 < q0 + 31) && (__ballot(carry > 0.f) != 0ull);
;     if (active) {
;       qk_tile(kcur, qf, S, l32, hh);
;       const bool full = kb * 64 + 63 < q0;
; #pragma unroll
;     ...
;         float st[16];
; #pragma unroll
;         for (int e = 0; e < 16; ++e) {
;           const float ez = ex2(S[kt2][e]);
;           const float r = __builtin_amdgcn_rcpf(1.f + ez);
;           const bool vis = full || (kb * 64 + kt2 * 32 + crow(e, hh) < qpos);
;           st[e] = vis ? r : 1.f;
;           S[kt2][e] = vis ? 1.f - r : 0.f;
;         }
;         float G[4], Go[4];
; #pragma unroll
;         for (int j = 0; j < 4; ++j) { G[j] = (st[4 * j] * st[4 * j + 1]) * (st[4 * j + 2] * st[4 * j + 3]); Go[j] = half_other(G[j], hh); }
;         float T = carry;
; #pragma unroll
;         for (int j = 3; j >= 0; --j) {
;           float run = hh ? T : T * Go[j];
; #pragma unroll
;           for (int e = 3; e >= 0; --e) {
;             const int idx = 4 * j + e;
;             S[kt2][idx] *= run;
;             run *= st[idx];
;           }
;           T *= G[j] * Go[j];
;         }
;         carry = T;
;       }
;       pv_tile(kcur + TS, S, O, l32, hh);
;     }
;   };
; #pragma unroll 1
;   for (int kb = kbs; kb >= 1; kb -= 2) {
;     const bf16_t* bcur = Ks + par * (4 * TS);
;     bf16_t* bnxt = Ks + (par ^ 1) * (4 * TS);
;     tile_commit(bnxt, pfk); tile_commit(bnxt + TS, pfv); tile_commit(bnxt + 2 * TS, pfk1); tile_commit(bnxt + 3 * TS, pfv1);
;     {
;       const int f0 = kb >= 5 ? kb - 4 : 1, f1 = kb >= 5 ? kb - 5 : 0;
;       pfk = tile_fetch(kb0 + (size_t)f0 * 64 * LDP_O, LDP_O); pfv = tile_fetch(vb0 + f0 * 64, SEQ);
;       pfk1 = tile_fetch(kb0 + (size_t)f1 * 64 * LDP_O, LDP_O); pfv1 = tile_fetch(vb0 + f1 * 64, SEQ);
;       __builtin_amdgcn_sched_barrier(0); }
.LBB0_485:
	s_mul_i32 s14, s12, 0x9000
	s_xor_b32 s12, s12, 1
	s_mul_i32 s0, s12, 0x9000
	v_add_u32_e32 v0, s0, v242
	s_add_i32 s9, s9, -2
	s_waitcnt vmcnt(3)
	ds_write_b128 v0, v[96:99]
	s_waitcnt vmcnt(2)
	ds_write_b128 v0, v[100:103] offset:9216
	s_waitcnt vmcnt(1)
	ds_write_b128 v0, v[104:107] offset:18432
	s_waitcnt vmcnt(0)
	ds_write_b128 v0, v[108:111] offset:27648
	s_max_u32 s0, s9, 5
	s_add_i32 s28, s0, -4
	s_lshl_b64 s[0:1], s[28:29], 18
	s_add_u32 s0, s44, s0
	s_addc_u32 s1, s45, s1
	global_load_dwordx4 v[96:99], v243, s[0:1] offset:2048
	s_lshl_b32 s28, s28, 6
	s_lshl_b64 s[0:1], s[28:29], 1
	s_add_u32 s0, s46, s0
	s_addc_u32 s1, s47, s1
	global_load_dwordx4 v[100:103], v244, s[0:1]
	s_sub_i32 s28, s9, 5
	s_max_i32 s28, s28, 0
	s_lshl_b64 s[0:1], s[28:29], 18
	s_add_u32 s0, s44, s0
	s_addc_u32 s1, s45, s1
	global_load_dwordx4 v[104:107], v243, s[0:1] offset:2048
	s_lshl_b32 s28, s28, 6
	s_lshl_b64 s[0:1], s[28:29], 1
	s_add_u32 s0, s46, s0
	s_addc_u32 s1, s47, s1
	global_load_dwordx4 v[108:111], v244, s[0:1]
	s_sub_i32 s0, s10, 63
	v_cmp_lt_i32_e32 vcc, s0, v119
	s_and_saveexec_b64 s[48:49], vcc
	s_cbranch_execz .LBB0_488
	v_cmp_lt_f32_e32 vcc, 0, v117
	s_cbranch_vccz .LBB0_488
	v_lshl_add_u32 v0, v121, 1, s14
	ds_read_b128 v[2:5], v0
	ds_read_b128 v[6:9], v0 offset:32
	ds_read_b128 v[10:13], v0 offset:64
	ds_read_b128 v[122:125], v0 offset:96
	ds_read_b128 v[64:67], v0 offset:4608
	ds_read_b128 v[126:129], v0 offset:4640
	ds_read_b128 v[130:133], v0 offset:4672
	ds_read_b128 v[134:137], v0 offset:4704
	s_waitcnt lgkmcnt(7)
	v_mfma_f32_32x32x16_bf16 v[48:63], v[2:5], v[80:83], 0
	s_waitcnt lgkmcnt(3)
	v_mfma_f32_32x32x16_bf16 v[64:79], v[64:67], v[80:83], 0
	v_mfma_f32_32x32x16_bf16 v[48:63], v[6:9], v[84:87], v[48:63]
	s_waitcnt lgkmcnt(2)
	v_mfma_f32_32x32x16_bf16 v[64:79], v[126:129], v[84:87], v[64:79]
	v_mfma_f32_32x32x16_bf16 v[48:63], v[10:13], v[88:91], v[48:63]
	s_waitcnt lgkmcnt(1)
	v_mfma_f32_32x32x16_bf16 v[64:79], v[130:133], v[88:91], v[64:79]
	v_mfma_f32_32x32x16_bf16 v[48:63], v[122:125], v[92:95], v[48:63]
	s_waitcnt lgkmcnt(0)
	v_mfma_f32_32x32x16_bf16 v[64:79], v[134:137], v[92:95], v[64:79]
	s_nop 10
	v_exp_f32_e32 v0, v64
	v_exp_f32_e32 v2, v65
	v_add_u32_e32 v13, s10, v113
	v_subrev_u32_e32 v3, 31, v13
	v_add_f32_e32 v0, 1.0, v0
	v_rcp_f32_e32 v0, v0
	v_cmp_lt_u32_e32 vcc, s10, v118
	s_cmp_eq_u64 vcc, exec
	s_cbranch_scc0 .Lsb_slow1
	v_add_f32_e32 v2, 1.0, v2
	v_mov_b32_e32 v3, v0
	v_sub_f32_e32 v0, 1.0, v0
	v_rcp_f32_e32 v64, v2
	v_exp_f32_e32 v4, v66
	v_sub_f32_e32 v65, 1.0, v64
	v_add_f32_e32 v2, 1.0, v4
	v_rcp_f32_e32 v66, v2
	v_exp_f32_e32 v4, v67
	v_sub_f32_e32 v67, 1.0, v66
	v_add_f32_e32 v2, 1.0, v4
	v_rcp_f32_e32 v2, v2
	v_exp_f32_e32 v4, v68
	v_mov_b32_e32 v68, v2
	v_sub_f32_e32 v122, 1.0, v2
	v_add_f32_e32 v2, 1.0, v4
	v_rcp_f32_e32 v5, v2
	v_exp_f32_e32 v4, v69
	v_sub_f32_e32 v12, 1.0, v5
	v_add_f32_e32 v2, 1.0, v4
	v_rcp_f32_e32 v14, v2
	v_exp_f32_e32 v4, v70
	v_sub_f32_e32 v15, 1.0, v14
	v_add_f32_e32 v2, 1.0, v4
	v_rcp_f32_e32 v69, v2
	v_exp_f32_e32 v4, v71
	v_sub_f32_e32 v70, 1.0, v69
	v_add_f32_e32 v2, 1.0, v4
	v_rcp_f32_e32 v71, v2
	v_exp_f32_e32 v4, v72
	v_sub_f32_e32 v72, 1.0, v71
	v_add_f32_e32 v2, 1.0, v4
	v_rcp_f32_e32 v6, v2
	v_exp_f32_e32 v4, v73
	v_sub_f32_e32 v73, 1.0, v6
	v_add_f32_e32 v2, 1.0, v4
	v_rcp_f32_e32 v8, v2
	v_exp_f32_e32 v4, v74
	v_sub_f32_e32 v74, 1.0, v8
	v_add_f32_e32 v2, 1.0, v4
	v_rcp_f32_e32 v2, v2
	v_exp_f32_e32 v4, v75
	v_mov_b32_e32 v75, v2
	v_sub_f32_e32 v123, 1.0, v2
	v_add_f32_e32 v2, 1.0, v4
	v_rcp_f32_e32 v2, v2
	v_exp_f32_e32 v4, v76
	v_mov_b32_e32 v76, v2
	v_sub_f32_e32 v124, 1.0, v2
	v_add_f32_e32 v2, 1.0, v4
	v_rcp_f32_e32 v7, v2
	v_exp_f32_e32 v4, v77
	v_sub_f32_e32 v77, 1.0, v7
	v_add_f32_e32 v2, 1.0, v4
	v_rcp_f32_e32 v2, v2
	v_exp_f32_e32 v4, v78
	v_mov_b32_e32 v78, v2
	v_sub_f32_e32 v125, 1.0, v2
	v_add_f32_e32 v2, 1.0, v4
	v_rcp_f32_e32 v2, v2
	v_exp_f32_e32 v4, v79
	v_mov_b32_e32 v79, v2
	v_sub_f32_e32 v126, 1.0, v2
	v_add_f32_e32 v2, 1.0, v4
	v_rcp_f32_e32 v127, v2
	v_mul_f32_e32 v7, v7, v78
	v_sub_f32_e32 v128, 1.0, v127
	v_mul_f32_e32 v2, v3, v64
	v_mul_f32_e32 v3, v66, v68
	v_mul_f32_e32 v4, v2, v3
	v_mov_b32_e32 v2, v4
	v_mov_b32_e32 v3, v4
	s_nop 1
	v_permlane32_swap_b32_e32 v2, v3
	v_cndmask_b32_e64 v2, v2, v3, s[40:41]
	v_mul_f32_e32 v3, v5, v14
	v_mul_f32_e32 v5, v69, v71
	v_mul_f32_e32 v3, v3, v5
	v_mov_b32_e32 v5, v3
	v_mov_b32_e32 v9, v3
	s_nop 1
	v_permlane32_swap_b32_e32 v5, v9
	v_cndmask_b32_e64 v5, v5, v9, s[40:41]
	v_mul_f32_e32 v9, v79, v127
	v_pk_mul_f32 v[6:7], v[6:7], v[8:9]
	v_mul_f32_e32 v10, v75, v76
	v_mov_b32_e32 v9, v7
	v_mov_b32_e32 v11, v7
	s_nop 1
	v_permlane32_swap_b32_e32 v9, v11
	v_cndmask_b32_e64 v11, v9, v11, s[40:41]
	v_pk_mul_f32 v[6:7], v[6:7], v[10:11]
	s_nop 0
	v_mov_b32_e32 v9, v6
	v_mov_b32_e32 v10, v6
	s_nop 1
	v_permlane32_swap_b32_e32 v9, v10
	v_cndmask_b32_e64 v116, v9, v10, s[40:41]
	v_mul_f32_e32 v9, v117, v11
	v_cndmask_b32_e64 v9, v117, v9, s[40:41]
	v_mul_f32_e32 v128, v128, v9
	v_mul_f32_e32 v9, v127, v9
	v_mul_f32_e32 v126, v126, v9
	v_mul_f32_e32 v9, v79, v9
	v_mul_f32_e32 v79, v125, v9
	v_mul_f32_e32 v9, v78, v9
	v_pk_mul_f32 v[6:7], v[6:7], v[116:117]
; DI float half_other(float x, int hh) { float a, b; half_swap(x, a, b); return hh ? a : b; }
; DI int crow(int reg, int hh) { return (reg & 3) + 8 * (reg >> 2) + 4 * hh; }
; DI float ex2(float x) { return __builtin_amdgcn_exp2f(x); }
; DI void sb_item(const bf16_t* __restrict__ P, const bf16_t* __restrict__ VT, bf16_t* __restrict__ Y, int item, char* lds) {
;     ...
;         float st[16];
; #pragma unroll
;         for (int e = 0; e < 16; ++e) {
;           const float ez = ex2(S[kt2][e]);
;           const float r = __builtin_amdgcn_rcpf(1.f + ez);
;           const bool vis = full || (kb * 64 + kt2 * 32 + crow(e, hh) < qpos);
;           st[e] = vis ? r : 1.f;
;           S[kt2][e] = vis ? 1.f - r : 0.f;
;         }
;         float G[4], Go[4];
; #pragma unroll
;         for (int j = 0; j < 4; ++j) { G[j] = (st[4 * j] * st[4 * j + 1]) * (st[4 * j + 2] * st[4 * j + 3]); Go[j] = half_other(G[j], hh); }
;         float T = carry;
; #pragma unroll
;         for (int j = 3; j >= 0; --j) {
;           float run = hh ? T : T * Go[j];
; #pragma unroll
;           for (int e = 3; e >= 0; --e) {
;             const int idx = 4 * j + e;
;             S[kt2][idx] *= run;
;             run *= st[idx];
;           }
;           T *= G[j] * Go[j];
;         }
;         carry = T;
;       }
;       pv_tile(kcur + TS, S, O, l32, hh);
	v_mul_f32_e32 v77, v77, v9
	v_mul_f32_e32 v9, v7, v116
	v_pk_mul_f32 v[10:11], v[6:7], v[6:7] op_sel:[0,1] op_sel_hi:[1,0]
	v_cndmask_b32_e64 v9, v7, v9, s[40:41]
	v_mul_f32_e32 v6, v10, v5
	v_exp_f32_e32 v7, v48
	v_cndmask_b32_e64 v6, v10, v6, s[40:41]
	v_mul_f32_e32 v72, v72, v6
	v_mul_f32_e32 v6, v71, v6
	v_mul_f32_e32 v70, v70, v6
	v_mul_f32_e32 v6, v69, v6
	v_mul_f32_e32 v69, v15, v6
	v_mul_f32_e32 v6, v14, v6
	v_mul_f32_e32 v14, v3, v5
	v_add_f32_e32 v3, 1.0, v7
	v_rcp_f32_e32 v3, v3
	v_mul_f32_e32 v78, v124, v9
	v_mul_f32_e32 v9, v76, v9
	v_exp_f32_e32 v5, v49
	v_mul_f32_e32 v76, v123, v9
	v_mul_f32_e32 v9, v75, v9
	v_mul_f32_e32 v8, v8, v9
	v_mul_f32_e32 v73, v73, v8
	v_mov_b32_e32 v8, v3
	v_sub_f32_e32 v75, 1.0, v3
	v_add_f32_e32 v3, 1.0, v5
	v_rcp_f32_e32 v3, v3
	v_exp_f32_e32 v5, v50
	v_mul_f32_e32 v71, v12, v6
	v_mov_b32_e32 v6, v3
	v_sub_f32_e32 v116, 1.0, v3
	v_add_f32_e32 v3, 1.0, v5
	v_rcp_f32_e32 v12, v3
	v_exp_f32_e32 v5, v51
	v_sub_f32_e32 v117, 1.0, v12
	v_add_f32_e32 v3, 1.0, v5
	v_rcp_f32_e32 v48, v3
	v_exp_f32_e32 v5, v52
	v_sub_f32_e32 v123, 1.0, v48
	v_add_f32_e32 v3, 1.0, v5
	v_rcp_f32_e32 v7, v3
	v_exp_f32_e32 v5, v53
	v_sub_f32_e32 v124, 1.0, v7
	v_add_f32_e32 v3, 1.0, v5
	v_rcp_f32_e32 v3, v3
	v_exp_f32_e32 v5, v54
	v_mov_b32_e32 v54, v3
	v_sub_f32_e32 v125, 1.0, v3
	v_add_f32_e32 v3, 1.0, v5
	v_rcp_f32_e32 v3, v3
	v_exp_f32_e32 v5, v55
	v_mov_b32_e32 v55, v3
	v_sub_f32_e32 v127, 1.0, v3
	v_add_f32_e32 v3, 1.0, v5
	v_rcp_f32_e32 v3, v3
	v_exp_f32_e32 v5, v56
	v_mov_b32_e32 v56, v3
	v_sub_f32_e32 v129, 1.0, v3
	v_add_f32_e32 v3, 1.0, v5
	v_rcp_f32_e32 v49, v3
	v_exp_f32_e32 v5, v57
	v_sub_f32_e32 v52, 1.0, v49
	v_add_f32_e32 v3, 1.0, v5
	v_rcp_f32_e32 v53, v3
	v_exp_f32_e32 v5, v58
	v_sub_f32_e32 v57, 1.0, v53
	v_add_f32_e32 v3, 1.0, v5
	v_rcp_f32_e32 v58, v3
	v_exp_f32_e32 v5, v59
	v_sub_f32_e32 v59, 1.0, v58
	v_add_f32_e32 v3, 1.0, v5
	v_rcp_f32_e32 v3, v3
	v_exp_f32_e32 v5, v60
	v_mov_b32_e32 v60, v3
	v_sub_f32_e32 v130, 1.0, v3
	v_add_f32_e32 v3, 1.0, v5
	v_rcp_f32_e32 v5, v3
	v_mul_f32_e32 v74, v74, v9
	v_exp_f32_e32 v9, v61
	v_exp_f32_e32 v11, v62
	v_sub_f32_e32 v61, 1.0, v5
	v_add_f32_e32 v3, 1.0, v9
	v_rcp_f32_e32 v3, v3
	v_mul_f32_e32 v7, v7, v54
	v_sub_f32_e32 v62, 1.0, v3
	v_add_f32_e32 v9, 1.0, v11
	v_rcp_f32_e32 v15, v9
	v_exp_f32_e32 v11, v63
	v_sub_f32_e32 v63, 1.0, v15
	v_add_f32_e32 v9, 1.0, v11
	v_rcp_f32_e32 v11, v9
	s_nop 0
	v_sub_f32_e32 v13, 1.0, v11
	v_mul_f32_e32 v9, v55, v56
	v_mul_f32_e32 v9, v7, v9
	v_mov_b32_e32 v7, v9
	v_mov_b32_e32 v50, v9
	s_nop 1
	v_permlane32_swap_b32_e32 v7, v50
	v_cndmask_b32_e64 v7, v7, v50, s[40:41]
	v_mul_f32_e32 v49, v49, v53
	v_mul_f32_e32 v50, v58, v60
	v_mul_f32_e32 v131, v49, v50
	v_mov_b32_e32 v49, v131
	v_mov_b32_e32 v50, v131
	s_nop 1
	v_permlane32_swap_b32_e32 v49, v50
	v_cndmask_b32_e64 v132, v49, v50, s[40:41]
	v_pk_mul_f32 v[50:51], v[14:15], v[10:11]
	v_pk_mul_f32 v[4:5], v[4:5], v[2:3]
	v_mul_f32_e32 v10, v50, v2
	v_cndmask_b32_e64 v10, v50, v10, s[40:41]
	v_mul_f32_e32 v122, v122, v10
	v_mul_f32_e32 v10, v68, v10
	v_mul_f32_e32 v67, v67, v10
	v_mul_f32_e32 v10, v66, v10
	v_mul_f32_e32 v65, v65, v10
	v_mul_f32_e32 v10, v64, v10
	v_pk_mul_f32 v[4:5], v[4:5], v[50:51]
	v_mul_f32_e32 v0, v0, v10
	v_mov_b32_e32 v2, v5
	v_mov_b32_e32 v10, v5
	s_nop 1
	v_permlane32_swap_b32_e32 v2, v10
	v_cndmask_b32_e64 v2, v2, v10, s[40:41]
	v_mul_f32_e32 v10, v4, v2
	v_mul_f32_e32 v2, v5, v2
	v_mul_f32_e32 v49, v4, v2
	v_mul_f32_e32 v2, v49, v132
	v_cndmask_b32_e64 v10, v4, v10, s[40:41]
	v_cndmask_b32_e64 v2, v49, v2, s[40:41]
	v_mul_f32_e32 v64, v13, v10
	v_mul_f32_e32 v10, v11, v10
	v_mul_f32_e32 v66, v130, v2
	v_mul_f32_e32 v2, v60, v2
	v_mul_f32_e32 v63, v63, v10
	v_mul_f32_e32 v10, v15, v10
	v_mul_f32_e32 v59, v59, v2
	v_mul_f32_e32 v2, v58, v2
	v_mul_f32_e32 v3, v3, v10
	v_mul_f32_e32 v57, v57, v2
	v_mul_f32_e32 v2, v53, v2
	v_mul_f32_e32 v13, v131, v132
	v_mul_f32_e32 v61, v61, v3
	v_mul_f32_e32 v58, v52, v2
	v_pk_mul_f32 v[2:3], v[12:13], v[48:49]
	v_pk_mul_f32 v[4:5], v[8:9], v[6:7]
	v_mul_f32_e32 v62, v62, v10
	v_pk_mul_f32 v[52:53], v[4:5], v[2:3]
	s_nop 0
	v_mov_b32_e32 v2, v52
	v_mov_b32_e32 v4, v52
	s_nop 1
	v_permlane32_swap_b32_e32 v2, v4
	v_cndmask_b32_e64 v60, v2, v4, s[40:41]
	v_mul_f32_e32 v2, v3, v7
	v_cndmask_b32_e64 v2, v3, v2, s[40:41]
	v_mul_f32_e32 v7, v129, v2
	v_mul_f32_e32 v2, v56, v2
	v_mul_f32_e32 v56, v127, v2
	v_mul_f32_e32 v2, v55, v2
	v_mul_f32_e32 v55, v125, v2
	v_mul_f32_e32 v2, v54, v2
	v_mul_f32_e32 v54, v124, v2
	v_mul_f32_e32 v2, v53, v60
	v_cndmask_b32_e64 v2, v53, v2, s[40:41]
	v_mul_f32_e32 v68, v123, v2
	v_mul_f32_e32 v2, v48, v2
	v_mul_f32_e32 v123, v117, v2
	v_mul_f32_e32 v117, v12, v2
	v_lshlrev_b32_e32 v2, 1, v113
	v_lshlrev_b32_e32 v3, 1, v120
	v_add3_u32 v12, s14, v2, v3
	v_add_u32_e32 v124, 0x2000, v12
	v_add_u32_e32 v125, 0x3000, v12
	ds_read2_b64 v[2:5], v124 offset0:128 offset1:130
	ds_read2_b64 v[8:11], v124 offset0:132 offset1:134
	ds_read2_b64 v[12:15], v125 offset0:192 offset1:194
	ds_read2_b64 v[48:51], v125 offset0:196 offset1:198
	v_mul_f32_e32 v52, v52, v60
	v_mul_f32_e32 v116, v116, v117
	v_mul_f32_e32 v6, v6, v117
	v_mul_f32_e32 v117, v52, v53
	v_mul_f32_e32 v6, v75, v6
	s_branch .Lsb_join1

; DI void pv_tile(const bf16_t* VTs, const f32x16 (&Pm)[2], f32x16 (&O)[2], int l32, int hh) {
; #pragma unroll
;   for (int kt2 = 0; kt2 < 2; ++kt2) {
;     u32x2 lo[2][2], hi[2][2];
; #pragma unroll
;     for (int t = 0; t < 2; ++t)
; #pragma unroll
;       for (int dt = 0; dt < 2; ++dt) {
;         const bf16_t* vp = &VTs[(dt * 32 + l32) * LDT + kt2 * 32 + 16 * t + 4 * hh];
;         lo[t][dt] = *(const u32x2*)vp; hi[t][dt] = *(const u32x2*)(vp + 8);
;       }
;     __builtin_amdgcn_sched_barrier(0);
;     __builtin_amdgcn_s_setprio(1);
; #pragma unroll
;     for (int t = 0; t < 2; ++t) {
;       u32x4 pk;
;       pk.x = pack2(Pm[kt2][8 * t + 0], Pm[kt2][8 * t + 1]); pk.y = pack2(Pm[kt2][8 * t + 2], Pm[kt2][8 * t + 3]);
;       pk.z = pack2(Pm[kt2][8 * t + 4], Pm[kt2][8 * t + 5]); pk.w = pack2(Pm[kt2][8 * t + 6], Pm[kt2][8 * t + 7]);
;       const bf16x8 pf = __builtin_bit_cast(bf16x8, pk);
; #pragma unroll
;       for (int dt = 0; dt < 2; ++dt) {
;         u32x4 vv; vv.x = lo[t][dt].x; vv.y = lo[t][dt].y; vv.z = hi[t][dt].x; vv.w = hi[t][dt].y;
;         O[dt] = MFMA32(__builtin_bit_cast(bf16x8, vv), pf, O[dt]);
;       }
;     }
;     __builtin_amdgcn_s_setprio(0);
;   }
; DI void sb_item(const bf16_t* __restrict__ P, const bf16_t* __restrict__ VT, bf16_t* __restrict__ Y, int item, char* lds) {
;     ...
;   auto do_tile = [&](int kb, const bf16_t* kcur) {
;     const bool active = (kb * 64 < q0 + 31) && (__ballot(carry > 0.f) != 0ull);
;     if (active) {
;       qk_tile(kcur, qf, S, l32, hh);
;       const bool full = kb * 64 + 63 < q0;
; #pragma unroll
;     ...
;         float st[16];
; #pragma unroll
;         for (int e = 0; e < 16; ++e) {
;           const float ez = ex2(S[kt2][e]);
;           const float r = __builtin_amdgcn_rcpf(1.f + ez);
;           const bool vis = full || (kb * 64 + kt2 * 32 + crow(e, hh) < qpos);
;           st[e] = vis ? r : 1.f;
;           S[kt2][e] = vis ? 1.f - r : 0.f;
;         }
;         float G[4], Go[4];
; #pragma unroll
;         for (int j = 0; j < 4; ++j) { G[j] = (st[4 * j] * st[4 * j + 1]) * (st[4 * j + 2] * st[4 * j + 3]); Go[j] = half_other(G[j], hh); }
;         float T = carry;
; #pragma unroll
;         for (int j = 3; j >= 0; --j) {
;           float run = hh ? T : T * Go[j];
; #pragma unroll
;           for (int e = 3; e >= 0; --e) {
;             const int idx = 4 * j + e;
;             S[kt2][idx] *= run;
.Lsb_join1:
	v_cvt_pk_bf16_f32 v52, v6, v116
	v_cvt_pk_bf16_f32 v53, v123, v68
	v_cvt_pk_bf16_f32 v54, v54, v55
	v_cvt_pk_bf16_f32 v55, v56, v7
	s_waitcnt lgkmcnt(3)
	s_nop 0
	v_mfma_f32_32x32x16_bf16 v[32:47], v[2:5], v[52:55], v[32:47]
	v_cvt_pk_bf16_f32 v2, v58, v57
	v_cvt_pk_bf16_f32 v3, v59, v66
	v_cvt_pk_bf16_f32 v4, v61, v62
	v_cvt_pk_bf16_f32 v5, v63, v64
	s_waitcnt lgkmcnt(1)
	v_mfma_f32_32x32x16_bf16 v[16:31], v[12:15], v[52:55], v[16:31]
	v_mfma_f32_32x32x16_bf16 v[32:47], v[8:11], v[2:5], v[32:47]
	s_waitcnt lgkmcnt(0)
	v_mfma_f32_32x32x16_bf16 v[16:31], v[48:51], v[2:5], v[16:31]
	ds_read2_b64 v[2:5], v124 offset0:136 offset1:138
	ds_read2_b64 v[6:9], v124 offset0:140 offset1:142
	ds_read2_b64 v[10:13], v125 offset0:200 offset1:202
	ds_read2_b64 v[48:51], v125 offset0:204 offset1:206
	v_cvt_pk_bf16_f32 v52, v0, v65
	v_cvt_pk_bf16_f32 v53, v67, v122
	v_cvt_pk_bf16_f32 v54, v71, v69
	v_cvt_pk_bf16_f32 v55, v70, v72
	s_waitcnt lgkmcnt(3)
	s_nop 0
	v_mfma_f32_32x32x16_bf16 v[32:47], v[2:5], v[52:55], v[32:47]
	v_cvt_pk_bf16_f32 v2, v73, v74
	v_cvt_pk_bf16_f32 v3, v76, v78
	v_cvt_pk_bf16_f32 v4, v77, v79
	v_cvt_pk_bf16_f32 v5, v126, v128
	s_waitcnt lgkmcnt(1)
	v_mfma_f32_32x32x16_bf16 v[16:31], v[10:13], v[52:55], v[16:31]
	v_mfma_f32_32x32x16_bf16 v[32:47], v[6:9], v[2:5], v[32:47]
	s_waitcnt lgkmcnt(0)
	v_mfma_f32_32x32x16_bf16 v[16:31], v[48:51], v[2:5], v[16:31]
.LBB0_488:
	s_or_b64 exec, exec, s[48:49]
	s_add_i32 s0, s10, 0xffffff81
	v_cmp_lt_i32_e32 vcc, s0, v119
	s_and_saveexec_b64 s[48:49], vcc
	s_cbranch_execz .LBB0_491
	v_cmp_lt_f32_e32 vcc, 0, v117
	s_cbranch_vccz .LBB0_491
	v_lshl_add_u32 v0, v121, 1, s14
	ds_read_b128 v[2:5], v0 offset:18432
	ds_read_b128 v[6:9], v0 offset:18464
	ds_read_b128 v[10:13], v0 offset:18496
	ds_read_b128 v[122:125], v0 offset:18528
	ds_read_b128 v[64:67], v0 offset:23040
	ds_read_b128 v[126:129], v0 offset:23072
	ds_read_b128 v[130:133], v0 offset:23104
	ds_read_b128 v[134:137], v0 offset:23136
	s_waitcnt lgkmcnt(7)
	v_mfma_f32_32x32x16_bf16 v[48:63], v[2:5], v[80:83], 0
	s_waitcnt lgkmcnt(3)
	v_mfma_f32_32x32x16_bf16 v[64:79], v[64:67], v[80:83], 0
	v_mfma_f32_32x32x16_bf16 v[48:63], v[6:9], v[84:87], v[48:63]
	s_waitcnt lgkmcnt(2)
	v_mfma_f32_32x32x16_bf16 v[64:79], v[126:129], v[84:87], v[64:79]
	v_mfma_f32_32x32x16_bf16 v[48:63], v[10:13], v[88:91], v[48:63]
	s_waitcnt lgkmcnt(1)
	v_mfma_f32_32x32x16_bf16 v[64:79], v[130:133], v[88:91], v[64:79]
	v_mfma_f32_32x32x16_bf16 v[48:63], v[122:125], v[92:95], v[48:63]
	s_waitcnt lgkmcnt(0)
	v_mfma_f32_32x32x16_bf16 v[64:79], v[134:137], v[92:95], v[64:79]
	s_nop 10
	v_exp_f32_e32 v0, v64
	v_add_u32_e32 v13, s10, v113
	s_sub_i32 s0, s10, 64
	v_add_u32_e32 v2, 0xffffffa1, v13
	v_cmp_lt_i32_e32 vcc, s0, v118
	s_cmp_eq_u64 vcc, exec
	s_cbranch_scc0 .Lsb_slow2
	v_add_f32_e32 v0, 1.0, v0
	v_exp_f32_e32 v2, v65
	v_rcp_f32_e32 v3, v0
	v_add_f32_e32 v2, 1.0, v2
	v_sub_f32_e32 v0, 1.0, v3
	v_rcp_f32_e32 v64, v2
	v_exp_f32_e32 v4, v66
	v_sub_f32_e32 v65, 1.0, v64
	v_add_f32_e32 v2, 1.0, v4
	v_rcp_f32_e32 v66, v2
	v_exp_f32_e32 v4, v67
	v_sub_f32_e32 v67, 1.0, v66
	v_add_f32_e32 v2, 1.0, v4
	v_rcp_f32_e32 v2, v2
	v_exp_f32_e32 v4, v68
	v_mov_b32_e32 v68, v2
	v_sub_f32_e32 v122, 1.0, v2
	v_add_f32_e32 v2, 1.0, v4
	v_rcp_f32_e32 v5, v2
	v_exp_f32_e32 v4, v69
	v_sub_f32_e32 v12, 1.0, v5
	v_add_f32_e32 v2, 1.0, v4
	v_rcp_f32_e32 v14, v2
	v_exp_f32_e32 v4, v70
	v_sub_f32_e32 v15, 1.0, v14
	v_add_f32_e32 v2, 1.0, v4
	v_rcp_f32_e32 v69, v2
	v_exp_f32_e32 v4, v71
	v_sub_f32_e32 v70, 1.0, v69
	v_add_f32_e32 v2, 1.0, v4
	v_rcp_f32_e32 v71, v2
	v_exp_f32_e32 v4, v72
	v_sub_f32_e32 v72, 1.0, v71
	v_add_f32_e32 v2, 1.0, v4
	v_rcp_f32_e32 v6, v2
	v_exp_f32_e32 v4, v73
	v_sub_f32_e32 v73, 1.0, v6
	v_add_f32_e32 v2, 1.0, v4
	v_rcp_f32_e32 v8, v2
	v_exp_f32_e32 v4, v74
	v_sub_f32_e32 v74, 1.0, v8
	v_add_f32_e32 v2, 1.0, v4
	v_rcp_f32_e32 v2, v2
	v_exp_f32_e32 v4, v75
	v_mov_b32_e32 v75, v2
	v_sub_f32_e32 v123, 1.0, v2
	v_add_f32_e32 v2, 1.0, v4
	v_rcp_f32_e32 v2, v2
	v_exp_f32_e32 v4, v76
	v_mov_b32_e32 v76, v2
	v_sub_f32_e32 v124, 1.0, v2
	v_add_f32_e32 v2, 1.0, v4
	v_rcp_f32_e32 v7, v2
	v_exp_f32_e32 v4, v77
	v_sub_f32_e32 v77, 1.0, v7
	v_add_f32_e32 v2, 1.0, v4
	v_rcp_f32_e32 v2, v2
	v_exp_f32_e32 v4, v78
	v_mov_b32_e32 v78, v2
	v_sub_f32_e32 v125, 1.0, v2
	v_add_f32_e32 v2, 1.0, v4
	v_rcp_f32_e32 v2, v2
	v_exp_f32_e32 v4, v79
	v_mov_b32_e32 v79, v2
	v_sub_f32_e32 v126, 1.0, v2
	v_add_f32_e32 v2, 1.0, v4
	v_rcp_f32_e32 v127, v2
	v_mul_f32_e32 v7, v7, v78
	v_sub_f32_e32 v128, 1.0, v127
	v_mul_f32_e32 v2, v3, v64
	v_mul_f32_e32 v3, v66, v68
	v_mul_f32_e32 v4, v2, v3
	v_mov_b32_e32 v2, v4
	v_mov_b32_e32 v3, v4
	s_nop 1
	v_permlane32_swap_b32_e32 v2, v3
	v_cndmask_b32_e64 v2, v2, v3, s[40:41]
	v_mul_f32_e32 v3, v5, v14
	v_mul_f32_e32 v5, v69, v71
	v_mul_f32_e32 v3, v3, v5
	v_mov_b32_e32 v5, v3
	v_mov_b32_e32 v9, v3
	s_nop 1
	v_permlane32_swap_b32_e32 v5, v9
	v_cndmask_b32_e64 v5, v5, v9, s[40:41]
	v_mul_f32_e32 v9, v79, v127
	v_pk_mul_f32 v[6:7], v[6:7], v[8:9]
	v_mul_f32_e32 v10, v75, v76
	v_mov_b32_e32 v9, v7
	v_mov_b32_e32 v11, v7
	s_nop 1
	v_permlane32_swap_b32_e32 v9, v11
	v_cndmask_b32_e64 v11, v9, v11, s[40:41]
	v_pk_mul_f32 v[6:7], v[6:7], v[10:11]
	s_nop 0
	v_mov_b32_e32 v9, v6
	v_mov_b32_e32 v10, v6
	s_nop 1
	v_permlane32_swap_b32_e32 v9, v10
	v_cndmask_b32_e64 v116, v9, v10, s[40:41]
	v_mul_f32_e32 v9, v117, v11
	v_cndmask_b32_e64 v9, v117, v9, s[40:41]
; DI float half_other(float x, int hh) { float a, b; half_swap(x, a, b); return hh ? a : b; }
; DI int crow(int reg, int hh) { return (reg & 3) + 8 * (reg >> 2) + 4 * hh; }
; DI float ex2(float x) { return __builtin_amdgcn_exp2f(x); }
; DI void sb_item(const bf16_t* __restrict__ P, const bf16_t* __restrict__ VT, bf16_t* __restrict__ Y, int item, char* lds) {
;     ...
;         float st[16];
; #pragma unroll
;         for (int e = 0; e < 16; ++e) {
;           const float ez = ex2(S[kt2][e]);
;           const float r = __builtin_amdgcn_rcpf(1.f + ez);
;           const bool vis = full || (kb * 64 + kt2 * 32 + crow(e, hh) < qpos);
;           st[e] = vis ? r : 1.f;
;           S[kt2][e] = vis ? 1.f - r : 0.f;
;         }
;         float G[4], Go[4];
; #pragma unroll
;         for (int j = 0; j < 4; ++j) { G[j] = (st[4 * j] * st[4 * j + 1]) * (st[4 * j + 2] * st[4 * j + 3]); Go[j] = half_other(G[j], hh); }
;         float T = carry;
; #pragma unroll
;         for (int j = 3; j >= 0; --j) {
;           float run = hh ? T : T * Go[j];
; #pragma unroll
;           for (int e = 3; e >= 0; --e) {
;             const int idx = 4 * j + e;
;             S[kt2][idx] *= run;
;             run *= st[idx];
;           }
;           T *= G[j] * Go[j];
;         }
;         carry = T;
;       }
;       pv_tile(kcur + TS, S, O, l32, hh);
	v_mul_f32_e32 v128, v128, v9
	v_mul_f32_e32 v9, v127, v9
	v_mul_f32_e32 v126, v126, v9
	v_mul_f32_e32 v9, v79, v9
	v_mul_f32_e32 v79, v125, v9
	v_mul_f32_e32 v9, v78, v9
	v_pk_mul_f32 v[6:7], v[6:7], v[116:117]
	v_mul_f32_e32 v77, v77, v9
	v_mul_f32_e32 v9, v7, v116
	v_pk_mul_f32 v[10:11], v[6:7], v[6:7] op_sel:[0,1] op_sel_hi:[1,0]
	v_cndmask_b32_e64 v9, v7, v9, s[40:41]
	v_mul_f32_e32 v6, v10, v5
	v_exp_f32_e32 v7, v48
	v_cndmask_b32_e64 v6, v10, v6, s[40:41]
	v_mul_f32_e32 v72, v72, v6
	v_mul_f32_e32 v6, v71, v6
	v_mul_f32_e32 v70, v70, v6
	v_mul_f32_e32 v6, v69, v6
	v_mul_f32_e32 v69, v15, v6
	v_mul_f32_e32 v6, v14, v6
	v_mul_f32_e32 v14, v3, v5
	v_add_f32_e32 v3, 1.0, v7
	v_rcp_f32_e32 v3, v3
	v_mul_f32_e32 v78, v124, v9
	v_mul_f32_e32 v9, v76, v9
	v_exp_f32_e32 v5, v49
	v_mul_f32_e32 v76, v123, v9
	v_mul_f32_e32 v9, v75, v9
	v_mul_f32_e32 v8, v8, v9
	v_mul_f32_e32 v73, v73, v8
	v_mov_b32_e32 v8, v3
	v_sub_f32_e32 v75, 1.0, v3
	v_add_f32_e32 v3, 1.0, v5
	v_rcp_f32_e32 v3, v3
	v_exp_f32_e32 v5, v50
	v_mul_f32_e32 v71, v12, v6
	v_mov_b32_e32 v6, v3
	v_sub_f32_e32 v116, 1.0, v3
	v_add_f32_e32 v3, 1.0, v5
	v_rcp_f32_e32 v12, v3
	v_exp_f32_e32 v5, v51
	v_sub_f32_e32 v117, 1.0, v12
	v_add_f32_e32 v3, 1.0, v5
	v_rcp_f32_e32 v48, v3
	v_exp_f32_e32 v5, v52
	v_sub_f32_e32 v123, 1.0, v48
	v_add_f32_e32 v3, 1.0, v5
	v_rcp_f32_e32 v7, v3
	v_exp_f32_e32 v5, v53
	v_sub_f32_e32 v124, 1.0, v7
	v_add_f32_e32 v3, 1.0, v5
	v_rcp_f32_e32 v3, v3
	v_exp_f32_e32 v5, v54
	v_mov_b32_e32 v54, v3
	v_sub_f32_e32 v125, 1.0, v3
	v_add_f32_e32 v3, 1.0, v5
	v_rcp_f32_e32 v3, v3
	v_exp_f32_e32 v5, v55
	v_mov_b32_e32 v55, v3
	v_sub_f32_e32 v127, 1.0, v3
	v_add_f32_e32 v3, 1.0, v5
	v_rcp_f32_e32 v3, v3
	v_exp_f32_e32 v5, v56
	v_mov_b32_e32 v56, v3
	v_sub_f32_e32 v129, 1.0, v3
	v_add_f32_e32 v3, 1.0, v5
	v_rcp_f32_e32 v49, v3
	v_exp_f32_e32 v5, v57
	v_sub_f32_e32 v52, 1.0, v49
	v_add_f32_e32 v3, 1.0, v5
	v_rcp_f32_e32 v53, v3
	v_exp_f32_e32 v5, v58
	v_sub_f32_e32 v57, 1.0, v53
	v_add_f32_e32 v3, 1.0, v5
	v_rcp_f32_e32 v58, v3
	v_exp_f32_e32 v5, v59
	v_sub_f32_e32 v59, 1.0, v58
	v_add_f32_e32 v3, 1.0, v5
	v_rcp_f32_e32 v3, v3
	v_exp_f32_e32 v5, v60
	v_mov_b32_e32 v60, v3
	v_sub_f32_e32 v130, 1.0, v3
	v_add_f32_e32 v3, 1.0, v5
	v_rcp_f32_e32 v5, v3
	v_mul_f32_e32 v74, v74, v9
	v_exp_f32_e32 v9, v61
	v_exp_f32_e32 v11, v62
	v_sub_f32_e32 v61, 1.0, v5
	v_add_f32_e32 v3, 1.0, v9
	v_rcp_f32_e32 v3, v3
	v_mul_f32_e32 v7, v7, v54
	v_sub_f32_e32 v62, 1.0, v3
	v_add_f32_e32 v9, 1.0, v11
	v_rcp_f32_e32 v15, v9
	v_exp_f32_e32 v11, v63
	v_sub_f32_e32 v63, 1.0, v15
	v_add_f32_e32 v9, 1.0, v11
	v_rcp_f32_e32 v11, v9
	s_nop 0
	v_sub_f32_e32 v13, 1.0, v11
	v_mul_f32_e32 v9, v55, v56
	v_mul_f32_e32 v9, v7, v9
	v_mov_b32_e32 v7, v9
	v_mov_b32_e32 v50, v9
	s_nop 1
	v_permlane32_swap_b32_e32 v7, v50
	v_cndmask_b32_e64 v7, v7, v50, s[40:41]
	v_mul_f32_e32 v49, v49, v53
	v_mul_f32_e32 v50, v58, v60
	v_mul_f32_e32 v131, v49, v50
	v_mov_b32_e32 v49, v131
	v_mov_b32_e32 v50, v131
	s_nop 1
	v_permlane32_swap_b32_e32 v49, v50
	v_cndmask_b32_e64 v132, v49, v50, s[40:41]
	v_pk_mul_f32 v[50:51], v[14:15], v[10:11]
	v_pk_mul_f32 v[4:5], v[4:5], v[2:3]
	v_mul_f32_e32 v10, v50, v2
	v_cndmask_b32_e64 v10, v50, v10, s[40:41]
	v_mul_f32_e32 v122, v122, v10
	v_mul_f32_e32 v10, v68, v10
	v_mul_f32_e32 v67, v67, v10
	v_mul_f32_e32 v10, v66, v10
	v_mul_f32_e32 v65, v65, v10
	v_mul_f32_e32 v10, v64, v10
	v_pk_mul_f32 v[4:5], v[4:5], v[50:51]
	v_mul_f32_e32 v0, v0, v10
	v_mov_b32_e32 v2, v5
	v_mov_b32_e32 v10, v5
	s_nop 1
	v_permlane32_swap_b32_e32 v2, v10
	v_cndmask_b32_e64 v2, v2, v10, s[40:41]
	v_mul_f32_e32 v10, v4, v2
	v_mul_f32_e32 v2, v5, v2
	v_mul_f32_e32 v49, v4, v2
	v_mul_f32_e32 v2, v49, v132
	v_cndmask_b32_e64 v10, v4, v10, s[40:41]
	v_cndmask_b32_e64 v2, v49, v2, s[40:41]
	v_mul_f32_e32 v64, v13, v10
	v_mul_f32_e32 v10, v11, v10
	v_mul_f32_e32 v66, v130, v2
	v_mul_f32_e32 v2, v60, v2
	v_mul_f32_e32 v63, v63, v10
	v_mul_f32_e32 v10, v15, v10
	v_mul_f32_e32 v59, v59, v2
	v_mul_f32_e32 v2, v58, v2
	v_mul_f32_e32 v3, v3, v10
	v_mul_f32_e32 v57, v57, v2
	v_mul_f32_e32 v2, v53, v2
	v_mul_f32_e32 v13, v131, v132
	v_mul_f32_e32 v61, v61, v3
	v_mul_f32_e32 v58, v52, v2
	v_pk_mul_f32 v[2:3], v[12:13], v[48:49]
	v_pk_mul_f32 v[4:5], v[8:9], v[6:7]
	v_mul_f32_e32 v62, v62, v10
	v_pk_mul_f32 v[52:53], v[4:5], v[2:3]
	s_nop 0
	v_mov_b32_e32 v2, v52
	v_mov_b32_e32 v4, v52
	s_nop 1
	v_permlane32_swap_b32_e32 v2, v4
	v_cndmask_b32_e64 v60, v2, v4, s[40:41]
	v_mul_f32_e32 v2, v3, v7
	v_cndmask_b32_e64 v2, v3, v2, s[40:41]
	v_mul_f32_e32 v7, v129, v2
	v_mul_f32_e32 v2, v56, v2
	v_mul_f32_e32 v56, v127, v2
	v_mul_f32_e32 v2, v55, v2
	v_mul_f32_e32 v55, v125, v2
	v_mul_f32_e32 v2, v54, v2
	v_mul_f32_e32 v54, v124, v2
	v_mul_f32_e32 v2, v53, v60
	v_cndmask_b32_e64 v2, v53, v2, s[40:41]
	v_mul_f32_e32 v68, v123, v2
	v_mul_f32_e32 v2, v48, v2
	v_mul_f32_e32 v123, v117, v2
	v_mul_f32_e32 v117, v12, v2
	v_lshlrev_b32_e32 v2, 1, v113
	v_lshlrev_b32_e32 v3, 1, v120
	v_add3_u32 v12, s14, v2, v3
	v_add_u32_e32 v124, 0x6800, v12
	v_add_u32_e32 v125, 0x7800, v12
	ds_read2_b64 v[2:5], v124 offset0:128 offset1:130
	ds_read2_b64 v[8:11], v124 offset0:132 offset1:134
	ds_read2_b64 v[12:15], v125 offset0:192 offset1:194
	ds_read2_b64 v[48:51], v125 offset0:196 offset1:198
	v_mul_f32_e32 v52, v52, v60
	v_mul_f32_e32 v116, v116, v117
	v_mul_f32_e32 v6, v6, v117
	v_mul_f32_e32 v117, v52, v53
	v_mul_f32_e32 v6, v75, v6
	s_branch .Lsb_join2
